# also drop redundant tile-head vmcnt(0) drain before K-loop (LDS-DMA protocol already covered by counted vmcnt(6)+barrier)
# speedup vs baseline: 1.0345x; 1.0024x over previous
.LBB0_951:
	s_ashr_i32 s15, s14, 31
	v_cmp_lt_i64_e32 vcc, s[16:17], v[140:141]
	s_lshl_b64 s[16:17], s[14:15], 20
	s_add_u32 s16, s68, s16
	s_addc_u32 s17, s69, s17
	s_and_b64 s[18:19], vcc, exec
	s_cselect_b32 s15, s17, s25
	s_cselect_b32 s21, s16, s24
	s_ashr_i32 s13, s12, 31
	s_lshl_b64 s[18:19], s[12:13], 20
	s_add_u32 s18, s31, s18
	s_addc_u32 s19, s33, s19
	s_and_b64 s[28:29], vcc, exec
	s_cselect_b32 s13, s19, s27
	s_cselect_b32 s46, s18, s26
	s_add_u32 s24, s24, 0x80080
	s_addc_u32 s25, s25, 0
	s_add_u32 s47, s26, 0x100
	v_mov_b32_e32 v0, 0
	s_addc_u32 s48, s27, 0
	s_mov_b32 s49, -2
	s_waitcnt lgkmcnt(0)
	v_mov_b32_e32 v1, v0
	v_mov_b32_e32 v2, v0
	v_mov_b32_e32 v3, v0
	v_mov_b32_e32 v4, v0
	v_mov_b32_e32 v5, v0
	v_mov_b32_e32 v6, v0
	v_mov_b32_e32 v7, v0
	v_mov_b32_e32 v16, v0
	v_mov_b32_e32 v17, v0
	v_mov_b32_e32 v18, v0
	v_mov_b32_e32 v19, v0
	v_mov_b32_e32 v20, v0
	v_mov_b32_e32 v21, v0
	v_mov_b32_e32 v22, v0
	v_mov_b32_e32 v23, v0
	v_mov_b32_e32 v32, v0
	v_mov_b32_e32 v33, v0
	v_mov_b32_e32 v34, v0
	v_mov_b32_e32 v35, v0
	v_mov_b32_e32 v36, v0
	v_mov_b32_e32 v37, v0
	v_mov_b32_e32 v38, v0
	v_mov_b32_e32 v39, v0
	v_mov_b32_e32 v48, v0
	v_mov_b32_e32 v49, v0
	v_mov_b32_e32 v50, v0
	v_mov_b32_e32 v51, v0
	v_mov_b32_e32 v52, v0
	v_mov_b32_e32 v53, v0
	v_mov_b32_e32 v54, v0
	v_mov_b32_e32 v55, v0
	v_mov_b32_e32 v8, v0
	v_mov_b32_e32 v9, v0
	v_mov_b32_e32 v10, v0
	v_mov_b32_e32 v11, v0
	v_mov_b32_e32 v12, v0
	v_mov_b32_e32 v13, v0
	v_mov_b32_e32 v14, v0
	v_mov_b32_e32 v15, v0
	v_mov_b32_e32 v24, v0
	v_mov_b32_e32 v25, v0
	v_mov_b32_e32 v26, v0
	v_mov_b32_e32 v27, v0
	v_mov_b32_e32 v28, v0
	v_mov_b32_e32 v29, v0
	v_mov_b32_e32 v30, v0
	v_mov_b32_e32 v31, v0
	v_mov_b32_e32 v40, v0
	v_mov_b32_e32 v41, v0
	v_mov_b32_e32 v42, v0
	v_mov_b32_e32 v43, v0
	v_mov_b32_e32 v44, v0
	v_mov_b32_e32 v45, v0
	v_mov_b32_e32 v46, v0
	v_mov_b32_e32 v47, v0
	v_mov_b32_e32 v56, v0
	v_mov_b32_e32 v57, v0
	v_mov_b32_e32 v58, v0
	v_mov_b32_e32 v59, v0
	v_mov_b32_e32 v60, v0
	v_mov_b32_e32 v61, v0
	v_mov_b32_e32 v62, v0
	v_mov_b32_e32 v63, v0
	v_mov_b32_e32 v64, v0
	v_mov_b32_e32 v65, v0
	v_mov_b32_e32 v66, v0
	v_mov_b32_e32 v67, v0
	v_mov_b32_e32 v68, v0
	v_mov_b32_e32 v69, v0
	v_mov_b32_e32 v70, v0
	v_mov_b32_e32 v71, v0
	v_mov_b32_e32 v80, v0
	v_mov_b32_e32 v81, v0
	v_mov_b32_e32 v82, v0
	v_mov_b32_e32 v83, v0
	v_mov_b32_e32 v84, v0
	v_mov_b32_e32 v85, v0
	v_mov_b32_e32 v86, v0
	v_mov_b32_e32 v87, v0
	v_mov_b32_e32 v96, v0
	v_mov_b32_e32 v97, v0
	v_mov_b32_e32 v98, v0
	v_mov_b32_e32 v99, v0
	v_mov_b32_e32 v100, v0
	v_mov_b32_e32 v101, v0
	v_mov_b32_e32 v102, v0
	v_mov_b32_e32 v103, v0
	v_mov_b32_e32 v112, v0
	v_mov_b32_e32 v113, v0
	v_mov_b32_e32 v114, v0
	v_mov_b32_e32 v115, v0
	v_mov_b32_e32 v116, v0
	v_mov_b32_e32 v117, v0
	v_mov_b32_e32 v118, v0
	v_mov_b32_e32 v119, v0
	v_mov_b32_e32 v72, v0
	v_mov_b32_e32 v73, v0
	v_mov_b32_e32 v74, v0
	v_mov_b32_e32 v75, v0
	v_mov_b32_e32 v76, v0
	v_mov_b32_e32 v77, v0
	v_mov_b32_e32 v78, v0
	v_mov_b32_e32 v79, v0
	v_mov_b32_e32 v88, v0
	v_mov_b32_e32 v89, v0
	v_mov_b32_e32 v90, v0
	v_mov_b32_e32 v91, v0
	v_mov_b32_e32 v92, v0
	v_mov_b32_e32 v93, v0
	v_mov_b32_e32 v94, v0
	v_mov_b32_e32 v95, v0
	v_mov_b32_e32 v104, v0
	v_mov_b32_e32 v105, v0
	v_mov_b32_e32 v106, v0
	v_mov_b32_e32 v107, v0
	v_mov_b32_e32 v108, v0
	v_mov_b32_e32 v109, v0
	v_mov_b32_e32 v110, v0
	v_mov_b32_e32 v111, v0
	v_mov_b32_e32 v120, v0
	v_mov_b32_e32 v121, v0
	v_mov_b32_e32 v122, v0
	v_mov_b32_e32 v123, v0
	v_mov_b32_e32 v124, v0
	v_mov_b32_e32 v125, v0
	v_mov_b32_e32 v126, v0
	v_mov_b32_e32 v127, v0

.LBB0_1038:
	s_ashr_i32 s23, s22, 31
	v_cmp_lt_i64_e32 vcc, s[0:1], v[140:141]
	s_lshl_b64 s[0:1], s[22:23], 20
	s_add_u32 s24, s6, s0
	s_addc_u32 s25, s7, s1
	s_and_b64 s[0:1], vcc, exec
	s_cselect_b32 s23, s25, s35
	s_cselect_b32 s56, s24, s34
	s_ashr_i32 s21, s20, 31
	s_lshl_b64 s[0:1], s[20:21], 20
	s_add_u32 s26, s36, s0
	s_addc_u32 s27, s37, s1
	s_and_b64 s[0:1], vcc, exec
	s_cselect_b32 s21, s27, s31
	s_cselect_b32 s57, s26, s30
	s_add_u32 s0, s34, 0x80080
	s_addc_u32 s1, s35, 0
	s_add_u32 s58, s30, 0x100
	v_mov_b32_e32 v0, 0
	s_addc_u32 s59, s31, 0
	s_mov_b32 s60, -2
	v_mov_b32_e32 v1, v0
	v_mov_b32_e32 v2, v0
	v_mov_b32_e32 v3, v0
	v_mov_b32_e32 v4, v0
	v_mov_b32_e32 v5, v0
	v_mov_b32_e32 v6, v0
	v_mov_b32_e32 v7, v0
	v_mov_b32_e32 v16, v0
	v_mov_b32_e32 v17, v0
	v_mov_b32_e32 v18, v0
	v_mov_b32_e32 v19, v0
	v_mov_b32_e32 v20, v0
	v_mov_b32_e32 v21, v0
	v_mov_b32_e32 v22, v0
	v_mov_b32_e32 v23, v0
	v_mov_b32_e32 v32, v0
	v_mov_b32_e32 v33, v0
	v_mov_b32_e32 v34, v0
	v_mov_b32_e32 v35, v0
	v_mov_b32_e32 v36, v0
	v_mov_b32_e32 v37, v0
	v_mov_b32_e32 v38, v0
	v_mov_b32_e32 v39, v0
	v_mov_b32_e32 v48, v0
	v_mov_b32_e32 v49, v0
	v_mov_b32_e32 v50, v0
	v_mov_b32_e32 v51, v0
	v_mov_b32_e32 v52, v0
	v_mov_b32_e32 v53, v0
	v_mov_b32_e32 v54, v0
	v_mov_b32_e32 v55, v0
	v_mov_b32_e32 v8, v0
	v_mov_b32_e32 v9, v0
	v_mov_b32_e32 v10, v0
	v_mov_b32_e32 v11, v0
	v_mov_b32_e32 v12, v0
	v_mov_b32_e32 v13, v0
	v_mov_b32_e32 v14, v0
	v_mov_b32_e32 v15, v0
	v_mov_b32_e32 v24, v0
	v_mov_b32_e32 v25, v0
	v_mov_b32_e32 v26, v0
	v_mov_b32_e32 v27, v0
	v_mov_b32_e32 v28, v0
	v_mov_b32_e32 v29, v0
	v_mov_b32_e32 v30, v0
	v_mov_b32_e32 v31, v0
	v_mov_b32_e32 v40, v0
	v_mov_b32_e32 v41, v0
	v_mov_b32_e32 v42, v0
	v_mov_b32_e32 v43, v0
	v_mov_b32_e32 v44, v0
	v_mov_b32_e32 v45, v0
	v_mov_b32_e32 v46, v0
	v_mov_b32_e32 v47, v0
	v_mov_b32_e32 v56, v0
	v_mov_b32_e32 v57, v0
	v_mov_b32_e32 v58, v0
	v_mov_b32_e32 v59, v0
	v_mov_b32_e32 v60, v0
	v_mov_b32_e32 v61, v0
	v_mov_b32_e32 v62, v0
	v_mov_b32_e32 v63, v0
	v_mov_b32_e32 v64, v0
	v_mov_b32_e32 v65, v0
	v_mov_b32_e32 v66, v0
	v_mov_b32_e32 v67, v0
	v_mov_b32_e32 v68, v0
	v_mov_b32_e32 v69, v0
	v_mov_b32_e32 v70, v0
	v_mov_b32_e32 v71, v0
	v_mov_b32_e32 v80, v0
	v_mov_b32_e32 v81, v0
	v_mov_b32_e32 v82, v0
	v_mov_b32_e32 v83, v0
	v_mov_b32_e32 v84, v0
	v_mov_b32_e32 v85, v0
	v_mov_b32_e32 v86, v0
	v_mov_b32_e32 v87, v0
	v_mov_b32_e32 v96, v0
	v_mov_b32_e32 v97, v0
	v_mov_b32_e32 v98, v0
	v_mov_b32_e32 v99, v0
	v_mov_b32_e32 v100, v0
	v_mov_b32_e32 v101, v0
	v_mov_b32_e32 v102, v0
	v_mov_b32_e32 v103, v0
	v_mov_b32_e32 v112, v0
	v_mov_b32_e32 v113, v0
	v_mov_b32_e32 v114, v0
	v_mov_b32_e32 v115, v0
	v_mov_b32_e32 v116, v0
	v_mov_b32_e32 v117, v0
	v_mov_b32_e32 v118, v0
	v_mov_b32_e32 v119, v0
	v_mov_b32_e32 v72, v0
	v_mov_b32_e32 v73, v0
	v_mov_b32_e32 v74, v0
	v_mov_b32_e32 v75, v0
	v_mov_b32_e32 v76, v0
	v_mov_b32_e32 v77, v0
	v_mov_b32_e32 v78, v0
	v_mov_b32_e32 v79, v0
	v_mov_b32_e32 v88, v0
	v_mov_b32_e32 v89, v0
	v_mov_b32_e32 v90, v0
	v_mov_b32_e32 v91, v0
	v_mov_b32_e32 v92, v0
	v_mov_b32_e32 v93, v0
	v_mov_b32_e32 v94, v0
	v_mov_b32_e32 v95, v0
	v_mov_b32_e32 v104, v0
	v_mov_b32_e32 v105, v0
	v_mov_b32_e32 v106, v0
	v_mov_b32_e32 v107, v0
	v_mov_b32_e32 v108, v0
	v_mov_b32_e32 v109, v0
	v_mov_b32_e32 v110, v0
	v_mov_b32_e32 v111, v0
	v_mov_b32_e32 v120, v0
	v_mov_b32_e32 v121, v0
	v_mov_b32_e32 v122, v0
	v_mov_b32_e32 v123, v0
	v_mov_b32_e32 v124, v0
	v_mov_b32_e32 v125, v0
	v_mov_b32_e32 v126, v0
	v_mov_b32_e32 v127, v0

.LBB0_1349:
	s_ashr_i32 s15, s14, 31
	v_cmp_lt_i64_e32 vcc, s[16:17], v[140:141]
	s_lshl_b64 s[16:17], s[14:15], 22
	s_add_u32 s16, s68, s16
	s_addc_u32 s17, s69, s17
	s_and_b64 s[18:19], vcc, exec
	s_cselect_b32 s15, s17, s25
	s_cselect_b32 s21, s16, s24
	s_ashr_i32 s13, s12, 31
	s_lshl_b64 s[18:19], s[12:13], 22
	s_add_u32 s18, s31, s18
	s_addc_u32 s19, s33, s19
	s_and_b64 s[28:29], vcc, exec
	s_cselect_b32 s13, s19, s27
	s_cselect_b32 s46, s18, s26
	s_add_u32 s24, s24, 0x200080
	s_addc_u32 s25, s25, 0
	s_add_u32 s47, s26, 0x100
	v_mov_b32_e32 v0, 0
	s_addc_u32 s48, s27, 0
	s_mov_b32 s49, -2
	s_waitcnt lgkmcnt(0)
	v_mov_b32_e32 v1, v0
	v_mov_b32_e32 v2, v0
	v_mov_b32_e32 v3, v0
	v_mov_b32_e32 v4, v0
	v_mov_b32_e32 v5, v0
	v_mov_b32_e32 v6, v0
	v_mov_b32_e32 v7, v0
	v_mov_b32_e32 v16, v0
	v_mov_b32_e32 v17, v0
	v_mov_b32_e32 v18, v0
	v_mov_b32_e32 v19, v0
	v_mov_b32_e32 v20, v0
	v_mov_b32_e32 v21, v0
	v_mov_b32_e32 v22, v0
	v_mov_b32_e32 v23, v0
	v_mov_b32_e32 v32, v0
	v_mov_b32_e32 v33, v0
	v_mov_b32_e32 v34, v0
	v_mov_b32_e32 v35, v0
	v_mov_b32_e32 v36, v0
	v_mov_b32_e32 v37, v0
	v_mov_b32_e32 v38, v0
	v_mov_b32_e32 v39, v0
	v_mov_b32_e32 v48, v0
	v_mov_b32_e32 v49, v0
	v_mov_b32_e32 v50, v0
	v_mov_b32_e32 v51, v0
	v_mov_b32_e32 v52, v0
	v_mov_b32_e32 v53, v0
	v_mov_b32_e32 v54, v0
	v_mov_b32_e32 v55, v0
	v_mov_b32_e32 v8, v0
	v_mov_b32_e32 v9, v0
	v_mov_b32_e32 v10, v0
	v_mov_b32_e32 v11, v0
	v_mov_b32_e32 v12, v0
	v_mov_b32_e32 v13, v0
	v_mov_b32_e32 v14, v0
	v_mov_b32_e32 v15, v0
	v_mov_b32_e32 v24, v0
	v_mov_b32_e32 v25, v0
	v_mov_b32_e32 v26, v0
	v_mov_b32_e32 v27, v0
	v_mov_b32_e32 v28, v0
	v_mov_b32_e32 v29, v0
	v_mov_b32_e32 v30, v0
	v_mov_b32_e32 v31, v0
	v_mov_b32_e32 v40, v0
	v_mov_b32_e32 v41, v0
	v_mov_b32_e32 v42, v0
	v_mov_b32_e32 v43, v0
	v_mov_b32_e32 v44, v0
	v_mov_b32_e32 v45, v0
	v_mov_b32_e32 v46, v0
	v_mov_b32_e32 v47, v0
	v_mov_b32_e32 v56, v0
	v_mov_b32_e32 v57, v0
	v_mov_b32_e32 v58, v0
	v_mov_b32_e32 v59, v0
	v_mov_b32_e32 v60, v0
	v_mov_b32_e32 v61, v0
	v_mov_b32_e32 v62, v0
	v_mov_b32_e32 v63, v0
	v_mov_b32_e32 v64, v0
	v_mov_b32_e32 v65, v0
	v_mov_b32_e32 v66, v0
	v_mov_b32_e32 v67, v0
	v_mov_b32_e32 v68, v0
	v_mov_b32_e32 v69, v0
	v_mov_b32_e32 v70, v0
	v_mov_b32_e32 v71, v0
	v_mov_b32_e32 v80, v0
	v_mov_b32_e32 v81, v0
	v_mov_b32_e32 v82, v0
	v_mov_b32_e32 v83, v0
	v_mov_b32_e32 v84, v0
	v_mov_b32_e32 v85, v0
	v_mov_b32_e32 v86, v0
	v_mov_b32_e32 v87, v0
	v_mov_b32_e32 v96, v0
	v_mov_b32_e32 v97, v0
	v_mov_b32_e32 v98, v0
	v_mov_b32_e32 v99, v0
	v_mov_b32_e32 v100, v0
	v_mov_b32_e32 v101, v0
	v_mov_b32_e32 v102, v0
	v_mov_b32_e32 v103, v0
	v_mov_b32_e32 v112, v0
	v_mov_b32_e32 v113, v0
	v_mov_b32_e32 v114, v0
	v_mov_b32_e32 v115, v0
	v_mov_b32_e32 v116, v0
	v_mov_b32_e32 v117, v0
	v_mov_b32_e32 v118, v0
	v_mov_b32_e32 v119, v0
	v_mov_b32_e32 v72, v0
	v_mov_b32_e32 v73, v0
	v_mov_b32_e32 v74, v0
	v_mov_b32_e32 v75, v0
	v_mov_b32_e32 v76, v0
	v_mov_b32_e32 v77, v0
	v_mov_b32_e32 v78, v0
	v_mov_b32_e32 v79, v0
	v_mov_b32_e32 v88, v0
	v_mov_b32_e32 v89, v0
	v_mov_b32_e32 v90, v0
	v_mov_b32_e32 v91, v0
	v_mov_b32_e32 v92, v0
	v_mov_b32_e32 v93, v0
	v_mov_b32_e32 v94, v0
	v_mov_b32_e32 v95, v0
	v_mov_b32_e32 v104, v0
	v_mov_b32_e32 v105, v0
	v_mov_b32_e32 v106, v0
	v_mov_b32_e32 v107, v0
	v_mov_b32_e32 v108, v0
	v_mov_b32_e32 v109, v0
	v_mov_b32_e32 v110, v0
	v_mov_b32_e32 v111, v0
	v_mov_b32_e32 v120, v0
	v_mov_b32_e32 v121, v0
	v_mov_b32_e32 v122, v0
	v_mov_b32_e32 v123, v0
	v_mov_b32_e32 v124, v0
	v_mov_b32_e32 v125, v0
	v_mov_b32_e32 v126, v0
	v_mov_b32_e32 v127, v0
